# final RMSNorm loop: gain vector hoisted, stores back to back; P1 modulate loop: all scale/shift loads issued up front, gain vector hoisted, no per-chunk vmcnt(0) drains
# speedup vs baseline: 1.0028x; 1.0028x over previous
.LBB0_50:
.LBB0_51:
	v_mov_b32_e32 v0, v228
	s_mov_b32 s4, 0x8800
	v_ashrrev_i32_e32 v1, 6, v0
	v_lshl_add_u32 v24, s2, 3, v1
	v_cmp_gt_i32_e32 vcc, s4, v24
	s_and_saveexec_b64 s[4:5], vcc
	s_cbranch_execz .LBB0_58
	v_mbcnt_lo_u32_b32 v1, -1, 0
	v_mbcnt_hi_u32_b32 v1, -1, v1
	v_and_b32_e32 v2, 64, v1
	v_add_u32_e32 v2, 64, v2
	v_xor_b32_e32 v3, 32, v1
	v_cmp_lt_i32_e32 vcc, v3, v2
	s_load_dword s6, s[0:1], 0xb0
	v_lshlrev_b32_e32 v0, 2, v0
	v_cndmask_b32_e32 v3, v1, v3, vcc
	v_lshlrev_b32_e32 v25, 2, v3
	v_xor_b32_e32 v3, 16, v1
	v_cmp_lt_i32_e32 vcc, v3, v2
	v_and_b32_e32 v0, 0xfc, v0
	v_mov_b32_e32 v5, 0
	v_cndmask_b32_e32 v3, v1, v3, vcc
	v_lshlrev_b32_e32 v26, 2, v3
	v_xor_b32_e32 v3, 8, v1
	v_cmp_lt_i32_e32 vcc, v3, v2
	v_lshlrev_b32_e32 v4, 2, v0
	v_lshl_add_u64 v[6:7], s[88:89], 0, v[4:5]
	v_cndmask_b32_e32 v3, v1, v3, vcc
	v_lshlrev_b32_e32 v27, 2, v3
	v_xor_b32_e32 v3, 4, v1
	v_cmp_lt_i32_e32 vcc, v3, v2
	v_or_b32_e32 v4, 0x200, v0
	v_or_b32_e32 v16, 0x300, v0
	v_cndmask_b32_e32 v3, v1, v3, vcc
	v_lshlrev_b32_e32 v28, 2, v3
	v_xor_b32_e32 v3, 2, v1
	v_cmp_lt_i32_e32 vcc, v3, v2
	s_waitcnt lgkmcnt(0)
	s_lshl_b32 s6, s6, 3
	s_mov_b64 s[8:9], 0
	v_cndmask_b32_e32 v3, v1, v3, vcc
	v_lshlrev_b32_e32 v29, 2, v3
	v_xor_b32_e32 v3, 1, v1
	v_cmp_lt_i32_e32 vcc, v3, v2
	v_or_b32_e32 v2, 0x100, v0
	s_mov_b32 s7, 0x78787879
	v_cndmask_b32_e32 v1, v1, v3, vcc
	v_lshlrev_b32_e32 v30, 2, v1
	s_movk_i32 s10, 0xff
	v_lshlrev_b32_e32 v8, 2, v0
	v_mov_b32_e32 v9, v5
	v_mov_b32_e32 v31, 0x358637bd
	s_mov_b32 s11, 0x800000
	s_mov_b64 s[12:13], 0x1000
	v_lshlrev_b32_e32 v10, 1, v0
	v_mov_b32_e32 v11, v5
	v_lshlrev_b32_e32 v12, 2, v2
	v_mov_b32_e32 v13, v5
	v_lshlrev_b32_e32 v14, 2, v4
	v_mov_b32_e32 v15, v5
	v_lshlrev_b32_e32 v16, 2, v16
	v_mov_b32_e32 v17, v5
	s_mov_b32 s16, 0x87ff
	global_load_dwordx4 v[72:75], v[6:7], off
	global_load_dwordx4 v[76:79], v[6:7], off offset:1024
	global_load_dwordx4 v[80:83], v[6:7], off offset:2048
	global_load_dwordx4 v[84:87], v[6:7], off offset:3072
	s_branch .LBB0_54
.LBB0_53:
	s_or_b64 exec, exec, s[14:15]
	v_lshlrev_b64 v[0:1], v22, v[0:1]
	v_lshl_add_u64 v[0:1], v[20:21], 0, v[0:1]
	v_lshlrev_b64 v[2:3], 12, v[2:3]
	v_lshl_add_u64 v[0:1], v[0:1], 0, v[2:3]
	v_lshl_add_u64 v[42:43], v[0:1], 0, v[8:9]
	global_load_dwordx4 v[20:23], v[42:43], off nt
	global_load_dwordx4 v[34:37], v[42:43], off offset:1024 nt
	global_load_dwordx4 v[38:41], v[42:43], off offset:2048 nt
	global_load_dwordx4 v[0:3], v[42:43], off offset:3072 nt
	v_lshl_add_u64 v[18:19], s[28:29], 0, v[18:19]
	v_lshl_add_u64 v[54:55], v[18:19], 0, s[12:13]
	v_lshl_add_u64 v[50:51], v[54:55], 0, v[8:9]
	global_load_dwordx4 v[42:45], v[50:51], off
	v_lshl_add_u64 v[56:57], v[18:19], 0, v[8:9]
	global_load_dwordx4 v[50:53], v[56:57], off
	v_lshl_add_u64 v[112:113], v[54:55], 0, v[12:13]
	global_load_dwordx4 v[88:91], v[112:113], off
	global_load_dwordx4 v[100:103], v[56:57], off offset:1024
	v_lshl_add_u64 v[114:115], v[54:55], 0, v[14:15]
	global_load_dwordx4 v[92:95], v[114:115], off
	global_load_dwordx4 v[104:107], v[56:57], off offset:2048
	v_lshl_add_u64 v[116:117], v[54:55], 0, v[16:17]
	global_load_dwordx4 v[96:99], v[116:117], off
	global_load_dwordx4 v[108:111], v[56:57], off offset:3072
	s_waitcnt vmcnt(11)
	v_mov_b32_e32 v58, v21
	s_waitcnt vmcnt(10)
	v_mov_b32_e32 v59, v35
	v_mov_b32_e32 v18, v20
	v_mov_b32_e32 v19, v34
	s_waitcnt vmcnt(9)
	v_mov_b32_e32 v66, v39
	s_waitcnt vmcnt(8)
	v_mov_b32_e32 v67, v1
	v_pk_mul_f32 v[58:59], v[58:59], v[58:59]
	v_mov_b32_e32 v60, v22
	v_mov_b32_e32 v61, v36
	v_mov_b32_e32 v64, v38
	v_mov_b32_e32 v65, v0
	v_pk_mul_f32 v[66:67], v[66:67], v[66:67]
	v_pk_fma_f32 v[18:19], v[18:19], v[18:19], v[58:59]
	v_mov_b32_e32 v62, v23
	v_mov_b32_e32 v63, v37
	v_mov_b32_e32 v68, v40
	v_mov_b32_e32 v69, v2
	v_pk_fma_f32 v[58:59], v[64:65], v[64:65], v[66:67]
	v_pk_fma_f32 v[18:19], v[60:61], v[60:61], v[18:19]
	v_mov_b32_e32 v70, v41
	v_mov_b32_e32 v71, v3
	v_pk_fma_f32 v[58:59], v[68:69], v[68:69], v[58:59]
	v_pk_fma_f32 v[18:19], v[62:63], v[62:63], v[18:19]
	v_pk_fma_f32 v[58:59], v[70:71], v[70:71], v[58:59]
	v_add_f32_e32 v4, v18, v19
	v_add_f32_e32 v4, v4, v58
	v_add_f32_e32 v4, v4, v59
	ds_bpermute_b32 v18, v25, v4
	s_waitcnt lgkmcnt(0)
	v_add_f32_e32 v4, v4, v18
	ds_bpermute_b32 v18, v26, v4
	s_waitcnt lgkmcnt(0)
	v_add_f32_e32 v4, v4, v18
	ds_bpermute_b32 v18, v27, v4
	s_waitcnt lgkmcnt(0)
	v_add_f32_e32 v4, v4, v18
	ds_bpermute_b32 v58, v28, v4
	v_ashrrev_i32_e32 v18, 13, v32
	v_add_u32_e32 v18, v18, v33
	v_ashrrev_i32_e32 v19, 31, v18
	s_waitcnt lgkmcnt(0)
	v_add_f32_e32 v4, v4, v58
	ds_bpermute_b32 v59, v29, v4
	v_mul_i32_i24_e32 v58, 0x4400, v18
	v_sub_u32_e32 v58, v24, v58
	v_lshlrev_b64 v[18:19], 26, v[18:19]
	v_lshl_add_u64 v[18:19], s[74:75], 0, v[18:19]
	s_waitcnt lgkmcnt(0)
	v_add_f32_e32 v4, v4, v59
	ds_bpermute_b32 v60, v30, v4
	v_ashrrev_i32_e32 v59, 31, v58
	v_lshlrev_b64 v[58:59], 11, v[58:59]
	v_lshl_add_u64 v[18:19], v[18:19], 0, v[58:59]
	v_add_u32_e32 v24, s6, v24
	s_waitcnt lgkmcnt(0)
	v_add_f32_e32 v4, v4, v60
	v_fmamk_f32 v4, v4, 0x3a800000, v31
	v_mul_f32_e32 v58, 0x4b800000, v4
	v_cmp_gt_f32_e32 vcc, s11, v4
	s_nop 1
	v_cndmask_b32_e32 v4, v4, v58, vcc
	v_rsq_f32_e32 v4, v4
	v_lshl_add_u64 v[58:59], v[18:19], 0, v[10:11]
	s_waitcnt vmcnt(0)
	v_pk_add_f32 v[18:19], v[42:43], 1.0 op_sel_hi:[1,0]
	v_pk_add_f32 v[42:43], v[44:45], 1.0 op_sel_hi:[1,0]
	v_mul_f32_e32 v44, 0x45800000, v4
	v_cndmask_b32_e32 v4, v4, v44, vcc
	v_pk_mul_f32 v[20:21], v[20:21], v[4:5] op_sel_hi:[1,0]
	v_pk_mul_f32 v[22:23], v[22:23], v[4:5] op_sel_hi:[1,0]
	v_pk_mul_f32 v[32:33], v[34:35], v[4:5] op_sel_hi:[1,0]
	v_pk_mul_f32 v[34:35], v[36:37], v[4:5] op_sel_hi:[1,0]
	v_pk_mul_f32 v[20:21], v[72:73], v[20:21]
	v_pk_mul_f32 v[22:23], v[74:75], v[22:23]
	v_pk_mul_f32 v[36:37], v[38:39], v[4:5] op_sel_hi:[1,0]
	v_pk_mul_f32 v[38:39], v[40:41], v[4:5] op_sel_hi:[1,0]
	v_pk_fma_f32 v[18:19], v[18:19], v[20:21], v[50:51]
	v_pk_fma_f32 v[20:21], v[42:43], v[22:23], v[52:53]
	v_pk_mul_f32 v[0:1], v[0:1], v[4:5] op_sel_hi:[1,0]
	v_pk_mul_f32 v[2:3], v[2:3], v[4:5] op_sel_hi:[1,0]
	v_cvt_pk_bf16_f32 v18, v18, v19
	v_cvt_pk_bf16_f32 v19, v20, v21
	global_store_dwordx2 v[58:59], v[18:19], off
	v_pk_mul_f32 v[118:119], v[32:33], v[76:77]
	v_pk_add_f32 v[32:33], v[88:89], 1.0 op_sel_hi:[1,0]
	v_pk_mul_f32 v[120:121], v[34:35], v[78:79]
	v_pk_add_f32 v[34:35], v[90:91], 1.0 op_sel_hi:[1,0]
	v_pk_fma_f32 v[118:119], v[118:119], v[32:33], v[100:101]
	v_pk_fma_f32 v[120:121], v[120:121], v[34:35], v[102:103]
	v_pk_mul_f32 v[122:123], v[36:37], v[80:81]
	v_pk_add_f32 v[32:33], v[92:93], 1.0 op_sel_hi:[1,0]
	v_cvt_pk_bf16_f32 v118, v118, v119
	v_cvt_pk_bf16_f32 v119, v120, v121
	global_store_dwordx2 v[58:59], v[118:119], off offset:512
	v_pk_mul_f32 v[124:125], v[38:39], v[82:83]
	v_pk_add_f32 v[34:35], v[94:95], 1.0 op_sel_hi:[1,0]
	v_pk_fma_f32 v[122:123], v[122:123], v[32:33], v[104:105]
	v_pk_fma_f32 v[124:125], v[124:125], v[34:35], v[106:107]
	v_pk_mul_f32 v[0:1], v[0:1], v[84:85]
	v_pk_add_f32 v[32:33], v[96:97], 1.0 op_sel_hi:[1,0]
	v_cvt_pk_bf16_f32 v122, v122, v123
	v_cvt_pk_bf16_f32 v123, v124, v125
	global_store_dwordx2 v[58:59], v[122:123], off offset:1024
	v_pk_mul_f32 v[2:3], v[2:3], v[86:87]
	v_pk_add_f32 v[34:35], v[98:99], 1.0 op_sel_hi:[1,0]
	v_pk_fma_f32 v[0:1], v[0:1], v[32:33], v[108:109]
	v_pk_fma_f32 v[2:3], v[2:3], v[34:35], v[110:111]
	v_cmp_lt_i32_e32 vcc, s16, v24
	s_or_b64 s[8:9], vcc, s[8:9]
	v_cvt_pk_bf16_f32 v0, v0, v1
	v_cvt_pk_bf16_f32 v1, v2, v3
	global_store_dwordx2 v[58:59], v[0:1], off offset:1536
	s_andn2_b64 exec, exec, s[8:9]
	s_cbranch_execz .LBB0_58

.LBB0_1287:
	s_cmp_lt_i32 s30, 18
	s_cselect_b64 s[0:1], -1, 0
	s_cmp_gt_i32 s31, 17
	s_cselect_b64 s[2:3], -1, 0
	s_and_b64 s[0:1], s[0:1], s[2:3]
	v_readlane_b32 s18, v251, 2
	v_readlane_b32 s20, v251, 4
	v_readlane_b32 s22, v251, 6
	v_readlane_b32 s10, v251, 10
	v_readlane_b32 s12, v251, 12
	v_readlane_b32 s14, v251, 14
	v_readlane_b32 s24, v251, 16
	v_readlane_b32 s26, v251, 18
	v_readlane_b32 s28, v251, 20
	v_readlane_b32 s34, v251, 22
	v_readlane_b32 s36, v251, 24
	v_readlane_b32 s38, v251, 26
	s_and_b64 vcc, exec, s[0:1]
	v_readlane_b32 s19, v251, 3
	v_readlane_b32 s21, v251, 5
	v_readlane_b32 s23, v251, 7
	v_readlane_b32 s11, v251, 11
	v_readlane_b32 s13, v251, 13
	v_readlane_b32 s15, v251, 15
	v_readlane_b32 s25, v251, 17
	v_readlane_b32 s27, v251, 19
	v_readlane_b32 s29, v251, 21
	v_readlane_b32 s35, v251, 23
	v_readlane_b32 s37, v251, 25
	v_readlane_b32 s39, v251, 27
	s_cbranch_vccz .LBB0_1345
	v_readlane_b32 s0, v252, 46
	v_ashrrev_i32_e32 v0, 6, v228
	s_nop 0
	v_add_u32_e32 v0, s0, v0
	s_mov_b32 s0, 0x8000
	v_cmp_gt_i32_e32 vcc, s0, v0
	s_and_saveexec_b64 s[0:1], vcc
	s_cbranch_execz .LBB0_1291
	v_and_b32_e32 v1, 64, v229
	v_add_u32_e32 v1, 64, v1
	v_xor_b32_e32 v2, 32, v229
	v_cmp_lt_i32_e32 vcc, v2, v1
	v_readlane_b32 s2, v253, 36
	v_readlane_b32 s3, v253, 37
	v_cndmask_b32_e32 v2, v229, v2, vcc
	v_lshlrev_b32_e32 v6, 2, v2
	v_xor_b32_e32 v2, 16, v229
	v_cmp_lt_i32_e32 vcc, v2, v1
	s_load_dword s2, s[2:3], 0x0
	v_mov_b32_e32 v5, 0
	v_cndmask_b32_e32 v2, v229, v2, vcc
	v_lshlrev_b32_e32 v7, 2, v2
	v_xor_b32_e32 v2, 8, v229
	v_cmp_lt_i32_e32 vcc, v2, v1
	s_waitcnt lgkmcnt(0)
	s_lshl_b32 s4, s2, 3
	s_mov_b64 s[2:3], 0
	v_cndmask_b32_e32 v2, v229, v2, vcc
	v_lshlrev_b32_e32 v8, 2, v2
	v_xor_b32_e32 v2, 4, v229
	v_cmp_lt_i32_e32 vcc, v2, v1
	v_mov_b32_e32 v12, 0x358637bd
	s_mov_b32 s5, 0x800000
	v_cndmask_b32_e32 v2, v229, v2, vcc
	v_lshlrev_b32_e32 v9, 2, v2
	v_xor_b32_e32 v2, 2, v229
	v_cmp_lt_i32_e32 vcc, v2, v1
	s_movk_i32 s6, 0x7fff
	s_nop 0
	v_cndmask_b32_e32 v2, v229, v2, vcc
	v_lshlrev_b32_e32 v10, 2, v2
	v_xor_b32_e32 v2, 1, v229
	v_cmp_lt_i32_e32 vcc, v2, v1
	s_nop 1
	v_cndmask_b32_e32 v1, v229, v2, vcc
	v_lshlrev_b32_e32 v11, 2, v1
	v_lshlrev_b32_e32 v1, 4, v228
	v_and_b32_e32 v4, 0x3f0, v1
	v_lshl_add_u64 v[2:3], s[48:49], 0, v[4:5]
	v_lshl_add_u64 v[4:5], s[50:51], 0, v[4:5]
	global_load_dwordx4 v[52:55], v[2:3], off
	global_load_dwordx4 v[56:59], v[2:3], off offset:1024
	global_load_dwordx4 v[60:63], v[2:3], off offset:2048
	global_load_dwordx4 v[64:67], v[2:3], off offset:3072
.LBB0_1290:
	v_ashrrev_i32_e32 v1, 31, v0
	v_lshlrev_b64 v[14:15], 12, v[0:1]
	v_lshl_add_u64 v[34:35], v[4:5], 0, v[14:15]
	global_load_dwordx4 v[14:17], v[34:35], off
	global_load_dwordx4 v[18:21], v[34:35], off offset:1024
	global_load_dwordx4 v[22:25], v[34:35], off offset:2048
	global_load_dwordx4 v[26:29], v[34:35], off offset:3072
	v_add_u32_e32 v0, s4, v0
	s_waitcnt vmcnt(3)
	v_mov_b32_e32 v38, v15
	s_waitcnt vmcnt(2)
	v_mov_b32_e32 v39, v19
	v_mov_b32_e32 v36, v14
	v_mov_b32_e32 v37, v18
	s_waitcnt vmcnt(1)
	v_mov_b32_e32 v46, v23
	s_waitcnt vmcnt(0)
	v_mov_b32_e32 v47, v27
	v_pk_mul_f32 v[38:39], v[38:39], v[38:39]
	v_mov_b32_e32 v40, v16
	v_mov_b32_e32 v41, v20
	v_mov_b32_e32 v44, v22
	v_mov_b32_e32 v45, v26
	v_pk_mul_f32 v[46:47], v[46:47], v[46:47]
	v_pk_fma_f32 v[36:37], v[36:37], v[36:37], v[38:39]
	v_mov_b32_e32 v42, v17
	v_mov_b32_e32 v43, v21
	v_mov_b32_e32 v48, v24
	v_mov_b32_e32 v49, v28
	v_pk_fma_f32 v[38:39], v[44:45], v[44:45], v[46:47]
	v_pk_fma_f32 v[36:37], v[40:41], v[40:41], v[36:37]
	v_mov_b32_e32 v50, v25
	v_mov_b32_e32 v51, v29
	v_pk_fma_f32 v[38:39], v[48:49], v[48:49], v[38:39]
	v_pk_fma_f32 v[36:37], v[42:43], v[42:43], v[36:37]
	v_pk_fma_f32 v[38:39], v[50:51], v[50:51], v[38:39]
	v_add_f32_e32 v1, v36, v37
	v_add_f32_e32 v1, v1, v38
	v_add_f32_e32 v1, v1, v39
	ds_bpermute_b32 v13, v6, v1
	s_waitcnt lgkmcnt(0)
	v_add_f32_e32 v1, v1, v13
	ds_bpermute_b32 v13, v7, v1
	s_waitcnt lgkmcnt(0)
	v_add_f32_e32 v1, v1, v13
	ds_bpermute_b32 v13, v8, v1
	s_waitcnt lgkmcnt(0)
	v_add_f32_e32 v1, v1, v13
	ds_bpermute_b32 v13, v9, v1
	s_waitcnt lgkmcnt(0)
	v_add_f32_e32 v1, v1, v13
	ds_bpermute_b32 v13, v10, v1
	s_waitcnt lgkmcnt(0)
	v_add_f32_e32 v1, v1, v13
	ds_bpermute_b32 v13, v11, v1
	s_waitcnt lgkmcnt(0)
	v_add_f32_e32 v1, v1, v13
	v_fmamk_f32 v1, v1, 0x3a800000, v12
	v_mul_f32_e32 v13, 0x4b800000, v1
	v_cmp_gt_f32_e32 vcc, s5, v1
	s_nop 1
	v_cndmask_b32_e32 v1, v1, v13, vcc
	v_rsq_f32_e32 v1, v1
	s_nop 0
	v_mul_f32_e32 v13, 0x45800000, v1
	v_cndmask_b32_e32 v36, v1, v13, vcc
	v_pk_mul_f32 v[14:15], v[14:15], v[36:37] op_sel_hi:[1,0]
	v_pk_mul_f32 v[16:17], v[16:17], v[36:37] op_sel_hi:[1,0]
	v_pk_mul_f32 v[18:19], v[18:19], v[36:37] op_sel_hi:[1,0]
	v_pk_mul_f32 v[20:21], v[20:21], v[36:37] op_sel_hi:[1,0]
	v_pk_mul_f32 v[22:23], v[22:23], v[36:37] op_sel_hi:[1,0]
	v_pk_mul_f32 v[24:25], v[24:25], v[36:37] op_sel_hi:[1,0]
	v_pk_mul_f32 v[26:27], v[26:27], v[36:37] op_sel_hi:[1,0]
	v_pk_mul_f32 v[28:29], v[28:29], v[36:37] op_sel_hi:[1,0]
	v_pk_mul_f32 v[14:15], v[52:53], v[14:15]
	v_pk_mul_f32 v[16:17], v[54:55], v[16:17]
	v_pk_mul_f32 v[18:19], v[56:57], v[18:19]
	v_pk_mul_f32 v[20:21], v[58:59], v[20:21]
	v_pk_mul_f32 v[22:23], v[22:23], v[60:61]
	v_pk_mul_f32 v[24:25], v[24:25], v[62:63]
	v_pk_mul_f32 v[26:27], v[26:27], v[64:65]
	v_pk_mul_f32 v[28:29], v[28:29], v[66:67]
	v_cmp_lt_i32_e32 vcc, s6, v0
	s_or_b64 s[2:3], vcc, s[2:3]
	global_store_dwordx4 v[34:35], v[14:17], off
	global_store_dwordx4 v[34:35], v[18:21], off offset:1024
	global_store_dwordx4 v[34:35], v[22:25], off offset:2048
	global_store_dwordx4 v[34:35], v[26:29], off offset:3072
	s_andn2_b64 exec, exec, s[2:3]
	s_cbranch_execnz .LBB0_1290
